# combo3 + prologue: silu(c) staging with all loads up front + static rebalancing of transpose items around the adaLN waves
# speedup vs baseline: 1.0053x; 1.0008x over previous
; __device__ __forceinline__ float siluf_(float x) { return x * sigmoidf_(x); }
; #define PBAR() do { if (hi - lo > 1) xcd_barrier(bar); asm volatile("" : "+v"(tid_)); lane_ = tid_ & 63; wave_ = __builtin_amdgcn_readfirstlane(tid_ >> 6); } while (0)
; __device__ __forceinline__ void phase_prologue(const In& in, unsigned char* ws, LAS unsigned char* lds, int tid, int wave, int lane) {
;     ...
;     for (int i = tid; i < NBATCH * D; i += 512) { const int b = i >> 11, k = i & 2047; condT[k * 8 + b] = siluf_(in.c[i]); }
; __global__ void __launch_bounds__(512, 2) fwd(Args a) {
;     ...
;     unsigned char* ws = a.ws;
;     unsigned* ctl = (unsigned*)(ws + WS_CTL);
;     const int lo = a.ph_lo, hi = a.ph_hi;
;     XcdBarrier bar; bar.bar = ctl + CW_BAR; bar.x = 0; bar.st = nullptr;
;     if (hi - lo > 1) bar = xcd_barrier_post(ctl + CW_BAR + a.li * XCD_BAR_WORDS, MISC + 8);
;     In in;
;     in.x = a.in[0]; in.c = a.in[1]; in.w_ada = a.in[2]; in.b_ada = a.in[3]; in.norm_gains = a.in[4]; in.w_gate = a.in[5]; in.w_up = a.in[6]; in.w_down = a.in[7]; in.w_in = a.in[8];
;     in.qk_gains = a.in[9]; in.diff_lambda = a.in[10]; in.diff_out_gain = a.in[11]; in.rel_bias = a.in[12]; in.lb_logits = a.in[13]; in.hgrn_gain = a.in[14]; in.gla_w_up = a.in[15];
;     in.gla_b = a.in[16]; in.gla_gain = a.in[17]; in.w_branch = a.in[18]; in.w_out = a.in[19];
;     float* out = a.out;
;     float* mod = (float*)(ws + WS_MOD);
;     bf16* H = (bf16*)(ws + WS_H); bf16* ACT = (bf16*)(ws + WS_ACT);
;     bf16* UA = (bf16*)(ws + WS_UA); bf16* UB = (bf16*)(ws + WS_UB); bf16* UC = (bf16*)(ws + WS_UC); bf16* UG = (bf16*)(ws + WS_UG); bf16* Y = (bf16*)(ws + WS_Y); _Float16* XH = (_Float16*)(ws + WS_XH);
;     const ScanBufs sb{(float*)(ws + WS_DB), (float*)(ws + WS_DC)};
;     int ph = 0;
;     ...
;     int tid_ = tid, lane_ = lane, wave_ = wave;
;     ...
;     for (int rep = 0; rep < (PROBE == 7 ? 2 : 1); ++rep) { if (rep) PBAR();
;     if (IN_(ph)) phase_prologue(in, ws, lds, tid_, wave_, lane_); }
.LBB0_9:
	v_writelane_b32 v252, s12, 11
	s_load_dwordx16 s[36:51], s[0:1], 0x0
	s_nop 0
	v_writelane_b32 v252, s13, 12
	v_writelane_b32 v252, s14, 13
	v_writelane_b32 v252, s15, 14
	v_writelane_b32 v252, s16, 15
	v_writelane_b32 v252, s17, 16
	v_writelane_b32 v252, s18, 17
	v_writelane_b32 v252, s19, 18
	s_waitcnt lgkmcnt(0)
	v_writelane_b32 v252, s36, 19
	s_nop 1
	v_writelane_b32 v252, s37, 20
	v_writelane_b32 v252, s38, 21
	v_writelane_b32 v252, s39, 22
	v_writelane_b32 v252, s40, 23
	v_writelane_b32 v252, s41, 24
	v_writelane_b32 v252, s42, 25
	v_writelane_b32 v252, s43, 26
	v_writelane_b32 v252, s44, 27
	v_writelane_b32 v252, s45, 28
	v_writelane_b32 v252, s46, 29
	v_writelane_b32 v252, s47, 30
	v_writelane_b32 v252, s48, 31
	v_writelane_b32 v252, s49, 32
	v_writelane_b32 v252, s50, 33
	v_writelane_b32 v252, s51, 34
	s_load_dwordx16 s[36:51], s[0:1], 0x40
	s_waitcnt lgkmcnt(0)
	v_writelane_b32 v252, s36, 35
	s_nop 1
	v_writelane_b32 v252, s37, 36
	v_writelane_b32 v252, s38, 37
	v_writelane_b32 v252, s39, 38
	v_writelane_b32 v252, s40, 39
	v_writelane_b32 v252, s41, 40
	v_writelane_b32 v252, s42, 41
	v_writelane_b32 v252, s43, 42
	v_writelane_b32 v252, s44, 43
	v_writelane_b32 v252, s45, 44
	v_writelane_b32 v252, s46, 45
	v_writelane_b32 v252, s47, 46
	v_writelane_b32 v252, s48, 47
	v_writelane_b32 v252, s49, 48
	v_writelane_b32 v252, s50, 49
	v_writelane_b32 v252, s51, 50
	s_nop 0
	v_readlane_b32 s40, v252, 11
	v_readlane_b32 s42, v252, 13
	v_readlane_b32 s43, v252, 14
	s_add_u32 s0, s42, 0x100000
	v_readlane_b32 s44, v252, 15
	s_addc_u32 s1, s43, 0
	v_readlane_b32 s41, v252, 12
	v_readlane_b32 s45, v252, 16
	v_readlane_b32 s46, v252, 17
	v_readlane_b32 s47, v252, 18
	v_writelane_b32 v252, s0, 51
	s_cmp_lt_i32 s44, 1
	s_nop 0
	v_writelane_b32 v252, s1, 52
	s_cselect_b64 s[0:1], -1, 0
	s_cmp_gt_i32 s45, 0
	s_cselect_b64 s[4:5], -1, 0
	s_and_b64 s[0:1], s[0:1], s[4:5]
	s_add_u32 s2, s42, 0x1a800000
	v_writelane_b32 v252, s2, 53
	s_addc_u32 s2, s43, 0
	v_writelane_b32 v252, s2, 54
	s_add_u32 s2, s42, 0x19000000
	v_writelane_b32 v252, s2, 55
	s_addc_u32 s2, s43, 0
	v_writelane_b32 v252, s2, 56
	s_add_u32 s2, s42, 0x10c00000
	v_writelane_b32 v252, s2, 57
	s_addc_u32 s2, s43, 0
	v_writelane_b32 v252, s2, 58
	s_add_u32 s2, s42, 0xb400000
	v_writelane_b32 v252, s2, 59
	s_addc_u32 s2, s43, 0
	v_writelane_b32 v252, s2, 60
	s_add_u32 s2, s42, 0x400000
	v_writelane_b32 v252, s2, 61
	s_addc_u32 s2, s43, 0
	v_writelane_b32 v252, s2, 62
	s_andn2_b64 vcc, exec, s[0:1]
	s_cbranch_vccnz .LBB0_50
	v_readlane_b32 s36, v252, 19
	v_lshlrev_b32_e32 v1, 3, v0
	v_lshlrev_b32_e32 v2, 2, v0
	v_mov_b32_e32 v3, 0
	v_readlane_b32 s38, v252, 21
	v_readlane_b32 s39, v252, 22
	s_mov_b64 s[0:1], 0
	s_mov_b64 s[4:5], 0x800
	v_lshl_add_u64 v[2:3], s[38:39], 0, v[2:3]
	s_movk_i32 s6, 0x3dff
	v_mov_b32_e32 v4, v1
	v_mov_b32_e32 v5, v0
	v_readlane_b32 s37, v252, 20
	v_readlane_b32 s40, v252, 23
	v_readlane_b32 s41, v252, 24
	v_readlane_b32 s42, v252, 25
	v_readlane_b32 s43, v252, 26
	v_readlane_b32 s44, v252, 27
	v_readlane_b32 s45, v252, 28
	v_readlane_b32 s46, v252, 29
	v_readlane_b32 s47, v252, 30
	v_readlane_b32 s48, v252, 31
	v_readlane_b32 s49, v252, 32
	v_readlane_b32 s50, v252, 33
	v_readlane_b32 s51, v252, 34
	s_mov_b64 s[4:5], 0x1000
	global_load_dword v20, v[2:3], off
	global_load_dword v21, v[2:3], off offset:2048
	v_lshl_add_u64 v[2:3], v[2:3], 0, s[4:5]
	global_load_dword v22, v[2:3], off
	global_load_dword v23, v[2:3], off offset:2048
	v_lshl_add_u64 v[2:3], v[2:3], 0, s[4:5]
	global_load_dword v24, v[2:3], off
	global_load_dword v25, v[2:3], off offset:2048
	v_lshl_add_u64 v[2:3], v[2:3], 0, s[4:5]
	global_load_dword v26, v[2:3], off
	global_load_dword v27, v[2:3], off offset:2048
	v_lshl_add_u64 v[2:3], v[2:3], 0, s[4:5]
	global_load_dword v28, v[2:3], off
	global_load_dword v29, v[2:3], off offset:2048
	v_lshl_add_u64 v[2:3], v[2:3], 0, s[4:5]
	global_load_dword v30, v[2:3], off
	global_load_dword v31, v[2:3], off offset:2048
	v_lshl_add_u64 v[2:3], v[2:3], 0, s[4:5]
	global_load_dword v32, v[2:3], off
	global_load_dword v33, v[2:3], off offset:2048
	v_lshl_add_u64 v[2:3], v[2:3], 0, s[4:5]
	global_load_dword v34, v[2:3], off
	global_load_dword v35, v[2:3], off offset:2048
	v_lshl_add_u64 v[2:3], v[2:3], 0, s[4:5]
	global_load_dword v36, v[2:3], off
	global_load_dword v37, v[2:3], off offset:2048
	v_lshl_add_u64 v[2:3], v[2:3], 0, s[4:5]
	global_load_dword v38, v[2:3], off
	global_load_dword v39, v[2:3], off offset:2048
	v_lshl_add_u64 v[2:3], v[2:3], 0, s[4:5]
	global_load_dword v40, v[2:3], off
	global_load_dword v41, v[2:3], off offset:2048
	v_lshl_add_u64 v[2:3], v[2:3], 0, s[4:5]
	global_load_dword v42, v[2:3], off
	global_load_dword v43, v[2:3], off offset:2048
	v_lshl_add_u64 v[2:3], v[2:3], 0, s[4:5]
	global_load_dword v44, v[2:3], off
	global_load_dword v45, v[2:3], off offset:2048
	v_lshl_add_u64 v[2:3], v[2:3], 0, s[4:5]
	global_load_dword v46, v[2:3], off
	global_load_dword v47, v[2:3], off offset:2048
	v_lshl_add_u64 v[2:3], v[2:3], 0, s[4:5]
	global_load_dword v48, v[2:3], off
	global_load_dword v49, v[2:3], off offset:2048
	v_lshl_add_u64 v[2:3], v[2:3], 0, s[4:5]
	global_load_dword v50, v[2:3], off
	global_load_dword v51, v[2:3], off offset:2048
	v_lshlrev_b32_e32 v6, 5, v0
	s_waitcnt vmcnt(28)
; __device__ __forceinline__ float siluf_(float x) { return x * sigmoidf_(x); }
; __device__ __forceinline__ void phase_prologue(const In& in, unsigned char* ws, LAS unsigned char* lds, int tid, int wave, int lane) {
;     ...
;     for (int i = tid; i < NBATCH * D; i += 512) { const int b = i >> 11, k = i & 2047; condT[k * 8 + b] = siluf_(in.c[i]); }
;     __syncthreads();
;     float* mod = (float*)(ws + WS_MOD);
;     if (wave < 3) {
;         const int id = (int)blockIdx.x + 256 * wave;
;         if (id < 576) {
	v_mul_f32_e32 v52, 0xbfb8aa3b, v20
	v_mul_f32_e32 v53, 0xbfb8aa3b, v21
	v_mul_f32_e32 v54, 0xbfb8aa3b, v22
	v_mul_f32_e32 v55, 0xbfb8aa3b, v23
	v_exp_f32_e32 v52, v52
	v_exp_f32_e32 v53, v53
	v_exp_f32_e32 v54, v54
	v_exp_f32_e32 v55, v55
	s_nop 0
	v_add_f32_e32 v52, 1.0, v52
	v_add_f32_e32 v53, 1.0, v53
	v_add_f32_e32 v54, 1.0, v54
	v_add_f32_e32 v55, 1.0, v55
	v_rcp_f32_e32 v52, v52
	v_rcp_f32_e32 v53, v53
	v_rcp_f32_e32 v54, v54
	v_rcp_f32_e32 v55, v55
	s_nop 0
	v_mul_f32_e32 v20, v20, v52
	v_mul_f32_e32 v21, v21, v53
	v_mul_f32_e32 v22, v22, v54
	v_mul_f32_e32 v23, v23, v55
	ds_write_b32 v6, v20
	ds_write_b32 v6, v21 offset:16384
	ds_write_b32 v6, v22 offset:32768
	ds_write_b32 v6, v23 offset:49152
	s_waitcnt vmcnt(24)
	v_mul_f32_e32 v52, 0xbfb8aa3b, v24
	v_mul_f32_e32 v53, 0xbfb8aa3b, v25
	v_mul_f32_e32 v54, 0xbfb8aa3b, v26
	v_mul_f32_e32 v55, 0xbfb8aa3b, v27
	v_exp_f32_e32 v52, v52
	v_exp_f32_e32 v53, v53
	v_exp_f32_e32 v54, v54
	v_exp_f32_e32 v55, v55
	s_nop 0
	v_add_f32_e32 v52, 1.0, v52
	v_add_f32_e32 v53, 1.0, v53
	v_add_f32_e32 v54, 1.0, v54
	v_add_f32_e32 v55, 1.0, v55
	v_rcp_f32_e32 v52, v52
	v_rcp_f32_e32 v53, v53
	v_rcp_f32_e32 v54, v54
	v_rcp_f32_e32 v55, v55
	s_nop 0
	v_mul_f32_e32 v24, v24, v52
	v_mul_f32_e32 v25, v25, v53
	v_mul_f32_e32 v26, v26, v54
	v_mul_f32_e32 v27, v27, v55
	ds_write_b32 v6, v24 offset:4
	ds_write_b32 v6, v25 offset:16388
	ds_write_b32 v6, v26 offset:32772
	ds_write_b32 v6, v27 offset:49156
	s_waitcnt vmcnt(20)
	v_mul_f32_e32 v52, 0xbfb8aa3b, v28
	v_mul_f32_e32 v53, 0xbfb8aa3b, v29
	v_mul_f32_e32 v54, 0xbfb8aa3b, v30
	v_mul_f32_e32 v55, 0xbfb8aa3b, v31
	v_exp_f32_e32 v52, v52
	v_exp_f32_e32 v53, v53
	v_exp_f32_e32 v54, v54
	v_exp_f32_e32 v55, v55
	s_nop 0
	v_add_f32_e32 v52, 1.0, v52
	v_add_f32_e32 v53, 1.0, v53
	v_add_f32_e32 v54, 1.0, v54
	v_add_f32_e32 v55, 1.0, v55
	v_rcp_f32_e32 v52, v52
	v_rcp_f32_e32 v53, v53
	v_rcp_f32_e32 v54, v54
	v_rcp_f32_e32 v55, v55
	s_nop 0
	v_mul_f32_e32 v28, v28, v52
	v_mul_f32_e32 v29, v29, v53
	v_mul_f32_e32 v30, v30, v54
	v_mul_f32_e32 v31, v31, v55
	ds_write_b32 v6, v28 offset:8
	ds_write_b32 v6, v29 offset:16392
	ds_write_b32 v6, v30 offset:32776
	ds_write_b32 v6, v31 offset:49160
	s_waitcnt vmcnt(16)
	v_mul_f32_e32 v52, 0xbfb8aa3b, v32
	v_mul_f32_e32 v53, 0xbfb8aa3b, v33
	v_mul_f32_e32 v54, 0xbfb8aa3b, v34
	v_mul_f32_e32 v55, 0xbfb8aa3b, v35
	v_exp_f32_e32 v52, v52
	v_exp_f32_e32 v53, v53
	v_exp_f32_e32 v54, v54
	v_exp_f32_e32 v55, v55
	s_nop 0
	v_add_f32_e32 v52, 1.0, v52
	v_add_f32_e32 v53, 1.0, v53
	v_add_f32_e32 v54, 1.0, v54
	v_add_f32_e32 v55, 1.0, v55
	v_rcp_f32_e32 v52, v52
	v_rcp_f32_e32 v53, v53
	v_rcp_f32_e32 v54, v54
	v_rcp_f32_e32 v55, v55
	s_nop 0
	v_mul_f32_e32 v32, v32, v52
	v_mul_f32_e32 v33, v33, v53
	v_mul_f32_e32 v34, v34, v54
	v_mul_f32_e32 v35, v35, v55
	ds_write_b32 v6, v32 offset:12
	ds_write_b32 v6, v33 offset:16396
	ds_write_b32 v6, v34 offset:32780
	ds_write_b32 v6, v35 offset:49164
	s_waitcnt vmcnt(12)
	v_mul_f32_e32 v52, 0xbfb8aa3b, v36
	v_mul_f32_e32 v53, 0xbfb8aa3b, v37
	v_mul_f32_e32 v54, 0xbfb8aa3b, v38
	v_mul_f32_e32 v55, 0xbfb8aa3b, v39
	v_exp_f32_e32 v52, v52
	v_exp_f32_e32 v53, v53
	v_exp_f32_e32 v54, v54
	v_exp_f32_e32 v55, v55
	s_nop 0
	v_add_f32_e32 v52, 1.0, v52
	v_add_f32_e32 v53, 1.0, v53
	v_add_f32_e32 v54, 1.0, v54
	v_add_f32_e32 v55, 1.0, v55
	v_rcp_f32_e32 v52, v52
	v_rcp_f32_e32 v53, v53
	v_rcp_f32_e32 v54, v54
	v_rcp_f32_e32 v55, v55
	s_nop 0
	v_mul_f32_e32 v36, v36, v52
	v_mul_f32_e32 v37, v37, v53
	v_mul_f32_e32 v38, v38, v54
	v_mul_f32_e32 v39, v39, v55
	ds_write_b32 v6, v36 offset:16
	ds_write_b32 v6, v37 offset:16400
	ds_write_b32 v6, v38 offset:32784
	ds_write_b32 v6, v39 offset:49168
	s_waitcnt vmcnt(8)
	v_mul_f32_e32 v52, 0xbfb8aa3b, v40
	v_mul_f32_e32 v53, 0xbfb8aa3b, v41
	v_mul_f32_e32 v54, 0xbfb8aa3b, v42
	v_mul_f32_e32 v55, 0xbfb8aa3b, v43
	v_exp_f32_e32 v52, v52
	v_exp_f32_e32 v53, v53
	v_exp_f32_e32 v54, v54
	v_exp_f32_e32 v55, v55
	s_nop 0
	v_add_f32_e32 v52, 1.0, v52
	v_add_f32_e32 v53, 1.0, v53
	v_add_f32_e32 v54, 1.0, v54
	v_add_f32_e32 v55, 1.0, v55
	v_rcp_f32_e32 v52, v52
	v_rcp_f32_e32 v53, v53
	v_rcp_f32_e32 v54, v54
	v_rcp_f32_e32 v55, v55
	s_nop 0
	v_mul_f32_e32 v40, v40, v52
	v_mul_f32_e32 v41, v41, v53
	v_mul_f32_e32 v42, v42, v54
	v_mul_f32_e32 v43, v43, v55
	ds_write_b32 v6, v40 offset:20
	ds_write_b32 v6, v41 offset:16404
	ds_write_b32 v6, v42 offset:32788
	ds_write_b32 v6, v43 offset:49172
	s_waitcnt vmcnt(4)
	v_mul_f32_e32 v52, 0xbfb8aa3b, v44
	v_mul_f32_e32 v53, 0xbfb8aa3b, v45
	v_mul_f32_e32 v54, 0xbfb8aa3b, v46
	v_mul_f32_e32 v55, 0xbfb8aa3b, v47
	v_exp_f32_e32 v52, v52
	v_exp_f32_e32 v53, v53
	v_exp_f32_e32 v54, v54
	v_exp_f32_e32 v55, v55
	s_nop 0
	v_add_f32_e32 v52, 1.0, v52
	v_add_f32_e32 v53, 1.0, v53
	v_add_f32_e32 v54, 1.0, v54
	v_add_f32_e32 v55, 1.0, v55
	v_rcp_f32_e32 v52, v52
	v_rcp_f32_e32 v53, v53
	v_rcp_f32_e32 v54, v54
	v_rcp_f32_e32 v55, v55
	s_nop 0
	v_mul_f32_e32 v44, v44, v52
	v_mul_f32_e32 v45, v45, v53
	v_mul_f32_e32 v46, v46, v54
	v_mul_f32_e32 v47, v47, v55
	ds_write_b32 v6, v44 offset:24
	ds_write_b32 v6, v45 offset:16408
	ds_write_b32 v6, v46 offset:32792
	ds_write_b32 v6, v47 offset:49176
	s_waitcnt vmcnt(0)
	v_mul_f32_e32 v52, 0xbfb8aa3b, v48
	v_mul_f32_e32 v53, 0xbfb8aa3b, v49
	v_mul_f32_e32 v54, 0xbfb8aa3b, v50
	v_mul_f32_e32 v55, 0xbfb8aa3b, v51
	v_exp_f32_e32 v52, v52
	v_exp_f32_e32 v53, v53
	v_exp_f32_e32 v54, v54
	v_exp_f32_e32 v55, v55
	s_nop 0
	v_add_f32_e32 v52, 1.0, v52
	v_add_f32_e32 v53, 1.0, v53
	v_add_f32_e32 v54, 1.0, v54
	v_add_f32_e32 v55, 1.0, v55
	v_rcp_f32_e32 v52, v52
	v_rcp_f32_e32 v53, v53
	v_rcp_f32_e32 v54, v54
	v_rcp_f32_e32 v55, v55
	s_nop 0
	v_mul_f32_e32 v48, v48, v52
	v_mul_f32_e32 v49, v49, v53
	v_mul_f32_e32 v50, v50, v54
	v_mul_f32_e32 v51, v51, v55
	ds_write_b32 v6, v48 offset:28
	ds_write_b32 v6, v49 offset:16412
	ds_write_b32 v6, v50 offset:32796
	ds_write_b32 v6, v51 offset:49180
	s_lshr_b32 s8, s9, 6
	s_cmpk_gt_u32 s9, 0xbf
	s_cselect_b64 s[0:1], -1, 0
	s_lshl_b32 s10, s8, 8
	s_add_i32 s10, s10, s67
	s_cmpk_gt_i32 s10, 0x23f
	s_cselect_b64 s[4:5], -1, 0
	s_or_b64 s[0:1], s[0:1], s[4:5]
	v_and_b32_e32 v16, 63, v0
	s_and_b64 vcc, exec, s[0:1]
	s_waitcnt lgkmcnt(0)
	s_barrier
; __device__ __forceinline__ void phase_prologue(const In& in, unsigned char* ws, LAS unsigned char* lds, int tid, int wave, int lane) {
;     ...
;             const int l = id / 288, cg = id % 288, col = cg * 64 + lane;
;             const float* W = in.w_ada + (size_t)l * D * NMOD + col;
;             float acc[8];
; #pragma unroll
;             for (int b = 0; b < 8; ++b) acc[b] = 0.f;
;             for (int k0 = 0; k0 < D; k0 += 16) {
;                 float w[16];
; #pragma unroll
;                 for (int j = 0; j < 16; ++j) w[j] = W[(size_t)(k0 + j) * NMOD];
	s_cbranch_vccnz .LBB0_16
	s_mul_hi_i32 s0, s10, 0x38e38e39
	s_lshr_b32 s1, s0, 31
	s_ashr_i32 s0, s0, 6
	s_add_i32 s9, s0, s1
	v_readlane_b32 s36, v252, 19
	s_mul_i32 s0, s9, 0x9000000
	v_lshl_or_b32 v2, s10, 6, v16
	s_mul_i32 s4, s9, 0x4800
	v_readlane_b32 s40, v252, 23
	s_mul_hi_i32 s1, s9, 0x9000000
	v_subrev_u32_e32 v2, s4, v2
	v_readlane_b32 s41, v252, 24
	s_add_u32 s0, s40, s0
	v_ashrrev_i32_e32 v3, 31, v2
	s_addc_u32 s1, s41, s1
	v_lshl_add_u64 v[2:3], v[2:3], 2, s[0:1]
	s_mov_b64 s[0:1], 0x90000
	v_mov_b32_e32 v4, 0
	v_lshl_add_u64 v[2:3], v[2:3], 0, s[0:1]
	s_mov_b32 s11, -16
	s_mov_b32 s12, 0
	s_mov_b64 s[6:7], 0x120000
	v_mov_b32_e32 v5, v4
	v_mov_b32_e32 v10, v4
	v_mov_b32_e32 v11, v4
	v_mov_b32_e32 v8, v4
	v_mov_b32_e32 v9, v4
	v_mov_b32_e32 v6, v4
	v_mov_b32_e32 v7, v4
	v_readlane_b32 s37, v252, 20
	v_readlane_b32 s38, v252, 21
	v_readlane_b32 s39, v252, 22
	v_readlane_b32 s42, v252, 25
	v_readlane_b32 s43, v252, 26
	v_readlane_b32 s44, v252, 27
	v_readlane_b32 s45, v252, 28
	v_readlane_b32 s46, v252, 29
	v_readlane_b32 s47, v252, 30
	v_readlane_b32 s48, v252, 31
	v_readlane_b32 s49, v252, 32
	v_readlane_b32 s50, v252, 33
	v_readlane_b32 s51, v252, 34
	v_readfirstlane_b32 s0, v2
	v_readfirstlane_b32 s1, v3
	v_lshlrev_b32_e32 v12, 2, v16
	s_nop 4
	s_sub_u32 s0, s0, 0x90000
	s_subb_u32 s1, s1, 0
	s_mov_b32 s6, 0x12000
	s_mov_b32 s12, 0
	s_mov_b32 s11, 31
	global_load_dword v20, v12, s[0:1]
	s_add_u32 s0, s0, s6
	s_addc_u32 s1, s1, 0
	global_load_dword v21, v12, s[0:1]
	s_add_u32 s0, s0, s6
	s_addc_u32 s1, s1, 0
	global_load_dword v22, v12, s[0:1]
	s_add_u32 s0, s0, s6
	s_addc_u32 s1, s1, 0
	global_load_dword v23, v12, s[0:1]
	s_add_u32 s0, s0, s6
	s_addc_u32 s1, s1, 0
	global_load_dword v24, v12, s[0:1]
	s_add_u32 s0, s0, s6
	s_addc_u32 s1, s1, 0
	global_load_dword v25, v12, s[0:1]
	s_add_u32 s0, s0, s6
	s_addc_u32 s1, s1, 0
	global_load_dword v26, v12, s[0:1]
	s_add_u32 s0, s0, s6
	s_addc_u32 s1, s1, 0
	global_load_dword v27, v12, s[0:1]
	s_add_u32 s0, s0, s6
	s_addc_u32 s1, s1, 0
	global_load_dword v28, v12, s[0:1]
	s_add_u32 s0, s0, s6
	s_addc_u32 s1, s1, 0
	global_load_dword v29, v12, s[0:1]
	s_add_u32 s0, s0, s6
	s_addc_u32 s1, s1, 0
	global_load_dword v30, v12, s[0:1]
	s_add_u32 s0, s0, s6
	s_addc_u32 s1, s1, 0
	global_load_dword v31, v12, s[0:1]
	s_add_u32 s0, s0, s6
	s_addc_u32 s1, s1, 0
	global_load_dword v32, v12, s[0:1]
	s_add_u32 s0, s0, s6
	s_addc_u32 s1, s1, 0
	global_load_dword v33, v12, s[0:1]
	s_add_u32 s0, s0, s6
	s_addc_u32 s1, s1, 0
	global_load_dword v34, v12, s[0:1]
	s_add_u32 s0, s0, s6
	s_addc_u32 s1, s1, 0
	global_load_dword v35, v12, s[0:1]
	s_add_u32 s0, s0, s6
	s_addc_u32 s1, s1, 0
	global_load_dword v36, v12, s[0:1]
	s_add_u32 s0, s0, s6
	s_addc_u32 s1, s1, 0
	global_load_dword v37, v12, s[0:1]
	s_add_u32 s0, s0, s6
	s_addc_u32 s1, s1, 0
	global_load_dword v38, v12, s[0:1]
	s_add_u32 s0, s0, s6
	s_addc_u32 s1, s1, 0
	global_load_dword v39, v12, s[0:1]
	s_add_u32 s0, s0, s6
	s_addc_u32 s1, s1, 0
	global_load_dword v40, v12, s[0:1]
	s_add_u32 s0, s0, s6
	s_addc_u32 s1, s1, 0
	global_load_dword v41, v12, s[0:1]
	s_add_u32 s0, s0, s6
	s_addc_u32 s1, s1, 0
	global_load_dword v42, v12, s[0:1]
	s_add_u32 s0, s0, s6
	s_addc_u32 s1, s1, 0
	global_load_dword v43, v12, s[0:1]
	s_add_u32 s0, s0, s6
	s_addc_u32 s1, s1, 0
	global_load_dword v44, v12, s[0:1]
	s_add_u32 s0, s0, s6
	s_addc_u32 s1, s1, 0
	global_load_dword v45, v12, s[0:1]
	s_add_u32 s0, s0, s6
	s_addc_u32 s1, s1, 0
	global_load_dword v46, v12, s[0:1]
	s_add_u32 s0, s0, s6
	s_addc_u32 s1, s1, 0
	global_load_dword v47, v12, s[0:1]
	s_add_u32 s0, s0, s6
	s_addc_u32 s1, s1, 0
	global_load_dword v48, v12, s[0:1]
	s_add_u32 s0, s0, s6
	s_addc_u32 s1, s1, 0
	global_load_dword v49, v12, s[0:1]
	s_add_u32 s0, s0, s6
	s_addc_u32 s1, s1, 0
	global_load_dword v50, v12, s[0:1]
	s_add_u32 s0, s0, s6
	s_addc_u32 s1, s1, 0
	global_load_dword v51, v12, s[0:1]
	s_add_u32 s0, s0, s6
	s_addc_u32 s1, s1, 0
	global_load_dword v52, v12, s[0:1]
	s_add_u32 s0, s0, s6
	s_addc_u32 s1, s1, 0
	global_load_dword v53, v12, s[0:1]
	s_add_u32 s0, s0, s6
	s_addc_u32 s1, s1, 0
	global_load_dword v54, v12, s[0:1]
	s_add_u32 s0, s0, s6
	s_addc_u32 s1, s1, 0
	global_load_dword v55, v12, s[0:1]
	s_add_u32 s0, s0, s6
	s_addc_u32 s1, s1, 0
	global_load_dword v56, v12, s[0:1]
	s_add_u32 s0, s0, s6
	s_addc_u32 s1, s1, 0
	global_load_dword v57, v12, s[0:1]
	s_add_u32 s0, s0, s6
	s_addc_u32 s1, s1, 0
	global_load_dword v58, v12, s[0:1]
	s_add_u32 s0, s0, s6
	s_addc_u32 s1, s1, 0
	global_load_dword v59, v12, s[0:1]
	s_add_u32 s0, s0, s6
	s_addc_u32 s1, s1, 0
	global_load_dword v60, v12, s[0:1]
	s_add_u32 s0, s0, s6
	s_addc_u32 s1, s1, 0
	global_load_dword v61, v12, s[0:1]
	s_add_u32 s0, s0, s6
	s_addc_u32 s1, s1, 0
	global_load_dword v62, v12, s[0:1]
	s_add_u32 s0, s0, s6
	s_addc_u32 s1, s1, 0
	global_load_dword v63, v12, s[0:1]
	s_add_u32 s0, s0, s6
	s_addc_u32 s1, s1, 0
	global_load_dword v64, v12, s[0:1]
	s_add_u32 s0, s0, s6
	s_addc_u32 s1, s1, 0
	global_load_dword v65, v12, s[0:1]
	s_add_u32 s0, s0, s6
	s_addc_u32 s1, s1, 0
	global_load_dword v66, v12, s[0:1]
	s_add_u32 s0, s0, s6
	s_addc_u32 s1, s1, 0
	global_load_dword v67, v12, s[0:1]
	s_add_u32 s0, s0, s6
	s_addc_u32 s1, s1, 0

; #define LAS __attribute__((address_space(3)))
; __device__ __forceinline__ void phase_prologue(const In& in, unsigned char* ws, LAS unsigned char* lds, int tid, int wave, int lane) {
;     ...
;     LAS float* scr = (LAS float*)(lds + 65536 + wave * 8704);
;     static_assert(65536 + 8 * 8704 <= RING_BYTES, "prologue LDS");
;     const int gw = (int)blockIdx.x * 8 + wave, NGW = (int)gridDim.x * 8;
;     constexpr int I_G = (D / 64) * (FF / 32);
;     constexpr int I_IN = (D / 64) * 512;
;     constexpr int I_B = (MIXW / 64) * (D / 32);
;     constexpr int I_O = (D / 64) * (D / 32);
;     constexpr int I_F = 256;
;     constexpr int PER_L = 6 * I_G + I_IN + 3 * I_B + I_O + I_F;
;     for (int it = gw; it < 2 * PER_L; it += NGW) {
;         const int l = it / PER_L; int r = it % PER_L;
.LBB0_16:
	s_lshl_b32 s0, s67, 3
	s_add_i32 s12, s8, s0
	s_mov_b32 s100, 1
	s_add_i32 s101, s12, 0x5080
	s_mov_b32 s12, s101
	s_cmp_lt_u32 s8, 2
	s_cbranch_scc1 .Lpro_rb_done
	s_cmp_eq_u32 s8, 2
	s_cbranch_scc0 .Lpro_rb_w37
	s_cmp_lt_u32 s67, 64
	s_cbranch_scc1 .Lpro_rb_done
	s_add_i32 s12, s67, 0x4c0
	s_branch .Lpro_rb_a
.Lpro_rb_w37:
	s_mul_i32 s12, s67, 5
	s_add_i32 s12, s12, s8
	s_add_i32 s12, s12, -3
.Lpro_rb_a:
	s_mov_b32 s100, 0
.Lpro_rb_done:
	v_readlane_b32 s40, v252, 11
	s_cmp_gt_i32 s12, 0x1b1ff
	v_readlane_b32 s41, v252, 12
	v_readlane_b32 s42, v252, 13
	v_readlane_b32 s43, v252, 14
	v_readlane_b32 s44, v252, 15
	v_readlane_b32 s45, v252, 16
	v_readlane_b32 s46, v252, 17
	v_readlane_b32 s47, v252, 18
	s_cbranch_scc1 .LBB0_50
	s_mulk_i32 s8, 0x2200
	s_add_i32 s0, s8, 0
	v_lshrrev_b32_e32 v3, 3, v16
	v_and_b32_e32 v26, 56, v1
	s_add_i32 s0, s0, 0x10000
	v_mul_u32_u24_e32 v1, 0x84, v26
	v_lshlrev_b32_e32 v2, 2, v3
	s_lshl_b32 s13, s3, 3
	s_cmp_lg_u32 s100, 0
	s_cselect_b32 s13, s13, 0x5c0
	v_add3_u32 v21, s0, v1, v2
	v_or_b32_e32 v1, 8, v3
	v_or_b32_e32 v5, 16, v3
	v_or_b32_e32 v7, 24, v3
	v_lshrrev_b32_e32 v18, 5, v16
	v_and_b32_e32 v20, 31, v0
	v_lshlrev_b32_e32 v2, 10, v3
	v_lshlrev_b32_e32 v4, 10, v1
	v_lshlrev_b32_e32 v6, 10, v5
	v_lshlrev_b32_e32 v8, 10, v7
	v_mul_u32_u24_e32 v10, 0x1600, v3
	s_add_u32 s15, s42, 0x13401000
	v_or_b32_e32 v19, 0xfff94000, v16
	s_mov_b32 s1, 0
	v_mov_b32_e32 v23, 0
	v_lshl_add_u32 v24, v20, 2, s0
	s_movk_i32 s14, 0x84
	v_lshlrev_b32_e32 v28, 11, v3
	v_lshlrev_b32_e32 v30, 11, v1
	v_lshlrev_b32_e32 v32, 11, v5
	v_lshlrev_b32_e32 v34, 11, v7
	v_mov_b32_e32 v1, v18
	s_addc_u32 s16, s43, 0
	s_mov_b32 s17, 0x10040
	s_mov_b32 s18, 0xa000
	v_mov_b32_e32 v25, 0x1000
	v_mov_b32_e32 v27, 0x2000
	v_mov_b32_e32 v29, 0x3000
	v_mov_b32_e32 v31, 0x4000
	v_mov_b32_e32 v33, 0x5000
	v_mov_b32_e32 v35, 0x6000
	v_mov_b32_e32 v48, 0x7000
	s_mov_b64 s[4:5], 0x2000
	v_lshlrev_b32_e32 v36, 1, v2
	v_lshlrev_b32_e32 v38, 1, v4
	v_lshlrev_b32_e32 v40, 1, v6
	v_lshlrev_b32_e32 v42, 1, v8
	v_lshlrev_b32_e32 v44, 1, v10
	s_mov_b32 s19, 0x16000
	s_mov_b32 s20, 0x2c000
	s_movk_i32 s21, 0x5800
	s_branch .LBB0_19
.LBB0_18:
	s_add_i32 s12, s12, s13
	s_cmp_lg_u32 s100, 0
	s_cbranch_scc1 .Lpro_rb_chkB
	s_cmp_lt_i32 s12, 0x5080
	s_cbranch_scc1 .LBB0_19
	s_mov_b32 s100, 1
	s_mov_b32 s12, s101
	s_lshl_b32 s13, s3, 3
.Lpro_rb_chkB:
	s_cmp_lt_i32 s12, 0x1b200
	s_cbranch_scc0 .LBB0_50
